# proj GEMM gets the same k-loop as wo in v58 (weight tile by LDS-DMA double buffer, activations register-staged two k-steps ahead)
# speedup vs baseline: 1.0338x; 1.0096x over previous
;   DI u16* hb() const { return (u16*)(ws + OFF_hb); }
; #define tid_opaque() tid_from(WAVE_S)
;   const int tid = tid_opaque(), lane = tid & 63;
;   u16* Xs = lds;
;   u16* Ys = lds + 128 * LSTR;
;   const int lr = tid >> 3, lc = (tid & 7) * 8;
;   const u16* xg = X + (size_t)lr * RS + lc;
;   const u16* yg = Y + (size_t)lr * RS + lc;
;   u32x4 xr[4], yr[4];
; #pragma unroll
;   for (int it = 0; it < 4; ++it) {
;     xr[it] = *(const u32x4*)(xg + (size_t)it * 32 * RS);
;     yr[it] = *(const u32x4*)(yg + (size_t)it * 32 * RS);
;   }
; #pragma unroll
;   for (int a = 0; a < TI; ++a)
; #pragma unroll
;     for (int b = 0; b < TJ; ++b)
; #pragma unroll
;       for (int r = 0; r < 16; ++r) acc[a][b][r] = 0.f;
;   const int fr = lane & 31, fh = (lane >> 5) * 8;
;   for (int kt = 0; kt < NKT; ++kt) {
;     __syncthreads();
; #pragma unroll
;     for (int it = 0; it < 4; ++it) {
;       *(u32x4*)(Xs + (lr + 32 * it) * LSTR + lc) = xr[it];
;       *(u32x4*)(Ys + (lr + 32 * it) * LSTR + lc) = yr[it];
;     }
;     __syncthreads();
;     if (kt + 1 < NKT) {
; #pragma unroll
;       for (int it = 0; it < 4; ++it) {
;         xr[it] = *(const u32x4*)(xg + (size_t)it * 32 * RS + (kt + 1) * 64);
;         yr[it] = *(const u32x4*)(yg + (size_t)it * 32 * RS + (kt + 1) * 64);
;       }
;     }
; DI void phase_proj(const Params& p, int layer, u16* lds, const int WAVE_S) {
;     ...
;   for (;;) {
;     const int slot = next_item(ctr, WAVE_S);
;     if (slot >= 768) break;
;     const int ft = slot % 12, tt = (slot / 12) * 8 + xcd;
;     f32x16 acc[2][2];
;     gemm_tile<2, 2>(W + (size_t)ft * 128 * DM, p.hb() + (size_t)tt * 128 * DM, acc, lds, wi0, wj0, WAVE_S);
.LBB0_76:
	s_or_b64 exec, exec, s[18:19]
	s_waitcnt lgkmcnt(0)
	s_barrier
	ds_read_b32 v2, v1 offset:40976
	s_movk_i32 s18, 0x2ff
	s_waitcnt lgkmcnt(0)
	v_cmp_lt_i32_e32 vcc, s18, v2
	v_readfirstlane_b32 s34, v2
	s_mov_b64 s[18:19], -1
	s_cbranch_vccnz .LBB0_71
	s_mul_hi_i32 s18, s34, 0x2aaaaaab
	s_lshr_b32 s19, s18, 31
	s_ashr_i32 s96, s18, 1
	s_add_i32 s96, s96, s19
	s_mul_i32 s18, s96, 12
	s_sub_i32 s48, s34, s18
	s_lshl_b32 s18, s96, 3
	s_ashr_i32 s49, s48, 31
	s_or_b32 s34, s18, s17
	s_lshl_b64 s[18:19], s[48:49], 18
	s_add_u32 s46, s36, s18
	v_mbcnt_lo_u32_b32 v14, -1, 0
	v_mbcnt_hi_u32_b32 v14, -1, v14
	s_addc_u32 s47, s37, s19
	v_add_u32_e32 v2, s33, v14
	s_ashr_i32 s35, s34, 31
	v_ashrrev_i32_e32 v2, 3, v2
	s_lshl_b64 s[50:51], s[34:35], 18
	v_ashrrev_i32_e32 v3, 31, v2
	s_add_u32 s50, s74, s50
	v_lshlrev_b64 v[4:5], 11, v[2:3]
	v_lshlrev_b32_e32 v3, 4, v14
	s_addc_u32 s51, s75, s51
	v_lshl_add_u64 v[6:7], s[46:47], 0, v[4:5]
	v_and_b32_e32 v8, 0x70, v3
	s_mov_b32 s100, s46
	s_mov_b32 s101, s47
	v_or_b32_e32 v138, v4, v8
	v_add_u32_e32 v139, s81, v138
	v_add_u32_e32 v140, s12, v138
	v_add_u32_e32 v125, s86, v138
	v_bfe_u32 v20, v2, 1, 3
	v_lshlrev_b32_e32 v20, 4, v20
	v_xor_b32_e32 v20, v8, v20
	v_lshl_or_b32 v106, v2, 7, v20
	s_lshr_b32 s52, s33, 6
	s_lshr_b32 s32, s52, 1
	s_lshl_b32 s52, s52, 12
	s_lshl_b32 s0, s32, 5
	s_add_u32 s53, s52, 0x8000
	s_add_u32 s53, s53, s0
	v_lshrrev_b32_e32 v21, 3, v14
	s_lshr_b32 s0, s33, 1
	v_add_u32_e32 v21, s0, v21
	v_lshlrev_b32_e32 v21, 11, v21
	v_and_b32_e32 v22, 7, v14
	v_lshrrev_b32_e32 v23, 4, v14
	v_xor_b32_e32 v22, v22, v23
	v_lshl_add_u32 v134, v22, 4, v21
	v_xor_b32_e32 v22, 4, v22
	v_lshl_add_u32 v135, v22, 4, v21
	v_add_u32_e32 v135, 0x3c00, v135
	v_add_u32_e32 v136, 0x7800, v134
	v_add_u32_e32 v137, 0x7800, v135
	v_and_b32_e32 v24, 31, v14
	v_lshlrev_b32_e32 v24, 7, v24
	v_bfe_u32 v25, v14, 1, 3
	v_lshrrev_b32_e32 v26, 5, v14
	v_xor_b32_e32 v25, v25, v26
	v_xor_b32_e32 v27, 0, v25
	v_lshl_add_u32 v104, v27, 4, v24
	v_xor_b32_e32 v27, 2, v25
	v_lshl_add_u32 v105, v27, 4, v24
	v_xor_b32_e32 v27, 4, v25
	v_lshl_add_u32 v108, v27, 4, v24
	v_xor_b32_e32 v27, 6, v25
	v_lshl_add_u32 v109, v27, 4, v24
	s_lshl_b32 s0, s32, 13
	s_mul_i32 s32, s32, 0x2020
	s_add_u32 s32, s32, 0x8000
	s_and_b32 s1, s33, 64
	s_lshl_b32 s1, s1, 7
	s_add_u32 s1, s1, 0x4000
	v_add_u32_e32 v156, s32, v104
	v_add_u32_e32 v160, s1, v104
	v_add_u32_e32 v157, s32, v105
	v_add_u32_e32 v161, s1, v105
	v_add_u32_e32 v158, s32, v108
	v_add_u32_e32 v162, s1, v108
	v_add_u32_e32 v159, s32, v109
	v_add_u32_e32 v163, s1, v109
	v_add_u32_e32 v104, s0, v104
	v_add_u32_e32 v105, s0, v105
	v_add_u32_e32 v108, s0, v108
	v_add_u32_e32 v109, s0, v109
	v_mov_b32_e32 v9, v1
	v_lshl_add_u64 v[6:7], v[6:7], 0, v[8:9]
	v_lshl_add_u64 v[10:11], s[50:51], 0, v[4:5]
	s_nop 0
	v_add_co_u32_e32 v10, vcc, s81, v6
	global_load_dwordx4 v[70:73], v138, s[50:51]
	global_load_dwordx4 v[78:81], v139, s[50:51]
	v_addc_co_u32_e32 v11, vcc, 0, v7, vcc
	v_add_co_u32_e32 v12, vcc, s81, v104
	v_and_b32_e32 v3, 31, v14
	s_nop 0
	v_addc_co_u32_e32 v13, vcc, 0, v105, vcc
	global_load_dwordx4 v[86:89], v140, s[50:51]
	global_load_dwordx4 v[94:97], v125, s[50:51]
	v_add_co_u32_e32 v10, vcc, s12, v6
	s_nop 0
	s_nop 0
	v_addc_co_u32_e32 v11, vcc, 0, v7, vcc
	v_add_co_u32_e32 v12, vcc, s12, v104
	s_mov_b64 s[46:47], 0
	s_nop 0
	v_addc_co_u32_e32 v13, vcc, 0, v105, vcc
	v_add_co_u32_e32 v6, vcc, s86, v6
	s_mov_b32 m0, s52
	s_nop 0
	global_load_lds_dwordx4 v134, s[100:101]
	global_load_lds_dwordx4 v135, s[100:101] offset:1024
	v_addc_co_u32_e32 v7, vcc, 0, v7, vcc
	v_add_co_u32_e32 v10, vcc, s86, v104
	s_nop 1
	v_addc_co_u32_e32 v11, vcc, 0, v105, vcc
	global_load_lds_dwordx4 v136, s[100:101] offset:2048
	global_load_lds_dwordx4 v137, s[100:101] offset:3072
	global_load_dwordx4 v[66:69], v138, s[50:51] offset:128
	global_load_dwordx4 v[74:77], v139, s[50:51] offset:128
	global_load_dwordx4 v[82:85], v140, s[50:51] offset:128
	global_load_dwordx4 v[90:93], v125, s[50:51] offset:128
	v_or_b32_e32 v6, v3, v126
	v_or_b32_e32 v3, v3, v127
	v_mul_u32_u24_e32 v8, 0x90, v3
	v_lshl_add_u64 v[2:3], s[18:19], 0, v[4:5]
	v_and_b32_e32 v4, 7, v14
	v_lshrrev_b32_e32 v7, 1, v14
	v_lshl_or_b32 v2, v4, 4, v2
	v_and_b32_e32 v7, 16, v7
	v_mul_lo_u32 v6, v6, s13
	s_nop 0
	v_mov_b32_e32 v2, 0
	s_nop 0
	s_nop 0
	v_mov_b32_e32 v3, v2
	v_mov_b32_e32 v4, v2
	v_mov_b32_e32 v5, v2
	v_mov_b32_e32 v6, v2
	v_mov_b32_e32 v7, v2
	v_mov_b32_e32 v8, v2
	v_mov_b32_e32 v9, v2
	v_mov_b32_e32 v10, v2
	v_mov_b32_e32 v11, v2
	v_mov_b32_e32 v12, v2
	v_mov_b32_e32 v13, v2
	v_mov_b32_e32 v14, v2
	v_mov_b32_e32 v15, v2
	v_mov_b32_e32 v16, v2
	v_mov_b32_e32 v17, v2
	v_mov_b32_e32 v34, v2
	v_mov_b32_e32 v35, v2
	v_mov_b32_e32 v36, v2
	v_mov_b32_e32 v37, v2
	s_waitcnt vmcnt(8)
	v_mov_b32_e32 v38, v2
	v_mov_b32_e32 v39, v2
	v_mov_b32_e32 v40, v2
	v_mov_b32_e32 v41, v2
	v_mov_b32_e32 v42, v2
	v_mov_b32_e32 v43, v2
	v_mov_b32_e32 v44, v2
	v_mov_b32_e32 v45, v2
	s_waitcnt vmcnt(10)
	v_mov_b32_e32 v46, v2
	v_mov_b32_e32 v47, v2
	v_mov_b32_e32 v48, v2
	v_mov_b32_e32 v49, v2
	v_mov_b32_e32 v18, v2
	v_mov_b32_e32 v19, v2
	v_mov_b32_e32 v20, v2
	v_mov_b32_e32 v21, v2
	v_mov_b32_e32 v22, v2
	v_mov_b32_e32 v23, v2
	v_mov_b32_e32 v24, v2
	v_mov_b32_e32 v25, v2
	v_mov_b32_e32 v26, v2
	v_mov_b32_e32 v27, v2
	v_mov_b32_e32 v28, v2
	v_mov_b32_e32 v29, v2
	v_mov_b32_e32 v30, v2
	v_mov_b32_e32 v31, v2
	v_mov_b32_e32 v32, v2
	v_mov_b32_e32 v33, v2
	v_mov_b32_e32 v50, v2
	v_mov_b32_e32 v51, v2
	v_mov_b32_e32 v52, v2
	v_mov_b32_e32 v53, v2
	s_waitcnt vmcnt(8)
	v_mov_b32_e32 v54, v2
	v_mov_b32_e32 v55, v2
	v_mov_b32_e32 v56, v2
	v_mov_b32_e32 v57, v2
	v_mov_b32_e32 v58, v2
	v_mov_b32_e32 v59, v2
	v_mov_b32_e32 v60, v2
	v_mov_b32_e32 v61, v2
	v_mov_b32_e32 v62, v2
	v_mov_b32_e32 v63, v2
	v_mov_b32_e32 v64, v2
	v_mov_b32_e32 v65, v2
	s_movk_i32 s98, 7
; #define MFMA32(a, b, c) __builtin_amdgcn_mfma_f32_32x32x16_bf16((a), (b), (c), 0, 0, 0)
;     ...
;   for (int kt = 0; kt < NKT; ++kt) {
;     __syncthreads();
; #pragma unroll
;     for (int it = 0; it < 4; ++it) {
;       *(u32x4*)(Xs + (lr + 32 * it) * LSTR + lc) = xr[it];
;       *(u32x4*)(Ys + (lr + 32 * it) * LSTR + lc) = yr[it];
;     }
;     __syncthreads();
;     if (kt + 1 < NKT) {
; #pragma unroll
;       for (int it = 0; it < 4; ++it) {
;         xr[it] = *(const u32x4*)(xg + (size_t)it * 32 * RS + (kt + 1) * 64);
;         yr[it] = *(const u32x4*)(yg + (size_t)it * 32 * RS + (kt + 1) * 64);
;       }
;     }
; #pragma unroll
;     for (int ks = 0; ks < 4; ++ks) {
;       bf16x8 af[TI], bfr[TJ];
; #pragma unroll
;       for (int a = 0; a < TI; ++a) af[a] = *(const bf16x8*)(Xs + (wi0 + a * 32 + fr) * LSTR + ks * 16 + fh);
; #pragma unroll
;       for (int b = 0; b < TJ; ++b) bfr[b] = *(const bf16x8*)(Ys + (wj0 + b * 32 + fr) * LSTR + ks * 16 + fh);
; #pragma unroll
;       for (int a = 0; a < TI; ++a)
; #pragma unroll
;         for (int b = 0; b < TJ; ++b) acc[a][b] = MFMA32(af[a], bfr[b], acc[a][b]);
;     }
;     __builtin_amdgcn_iglp_opt(1);
;   }
.Lwd_k_pj:
	s_barrier
	s_waitcnt vmcnt(11)
	ds_write_b128 v106, v[70:73] offset:16384
	s_waitcnt vmcnt(10)
	ds_write_b128 v106, v[78:81] offset:20480
	s_waitcnt vmcnt(9)
	ds_write_b128 v106, v[86:89] offset:24576
	s_waitcnt vmcnt(8)
	ds_write_b128 v106, v[94:97] offset:28672
	s_waitcnt vmcnt(4)
	s_add_u32 s100, s100, 0x80
	s_addc_u32 s101, s101, 0
	s_mov_b32 m0, s53
	s_nop 0
	global_load_lds_dwordx4 v134, s[100:101]
	global_load_lds_dwordx4 v135, s[100:101] offset:1024
	global_load_lds_dwordx4 v136, s[100:101] offset:2048
	global_load_lds_dwordx4 v137, s[100:101] offset:3072
	s_waitcnt lgkmcnt(0)
	s_barrier
	ds_read_b128 v[112:115], v104 offset:4096
	ds_read_b128 v[120:123], v104
	ds_read_b128 v[116:119], v160 offset:4096
	ds_read_b128 v[148:151], v160
	ds_read_b128 v[142:145], v105
	ds_read_b128 v[152:155], v161
	s_waitcnt lgkmcnt(2)
	v_mfma_f32_32x32x16_bf16 v[34:49], v[112:115], v[148:151], v[34:49]
	v_mfma_f32_32x32x16_bf16 v[2:17], v[112:115], v[116:119], v[2:17]
	ds_read_b128 v[112:115], v105 offset:4096
	v_mfma_f32_32x32x16_bf16 v[18:33], v[120:123], v[116:119], v[18:33]
	ds_read_b128 v[116:119], v161 offset:4096
	s_waitcnt lgkmcnt(1)
	v_mfma_f32_32x32x16_bf16 v[34:49], v[112:115], v[152:155], v[34:49]
	s_waitcnt lgkmcnt(0)
	v_mfma_f32_32x32x16_bf16 v[2:17], v[112:115], v[116:119], v[2:17]
	ds_read_b128 v[112:115], v108
	v_mfma_f32_32x32x16_bf16 v[18:33], v[142:145], v[116:119], v[18:33]
	ds_read_b128 v[116:119], v108 offset:4096
	v_mfma_f32_32x32x16_bf16 v[50:65], v[120:123], v[148:151], v[50:65]
	ds_read_b128 v[120:123], v162
	v_mfma_f32_32x32x16_bf16 v[50:65], v[142:145], v[152:155], v[50:65]
	ds_read_b128 v[142:145], v162 offset:4096
	s_waitcnt lgkmcnt(1)
	v_mfma_f32_32x32x16_bf16 v[50:65], v[112:115], v[120:123], v[50:65]
	s_waitcnt lgkmcnt(0)
	v_mfma_f32_32x32x16_bf16 v[18:33], v[112:115], v[142:145], v[18:33]
	ds_read_b128 v[112:115], v109
	v_mfma_f32_32x32x16_bf16 v[34:49], v[116:119], v[120:123], v[34:49]
	v_mfma_f32_32x32x16_bf16 v[2:17], v[116:119], v[142:145], v[2:17]
	ds_read_b128 v[116:119], v109 offset:4096
	ds_read_b128 v[120:123], v163
	ds_read_b128 v[142:145], v163 offset:4096
	s_add_u32 s50, s50, 0x80
	s_addc_u32 s51, s51, 0
	global_load_dwordx4 v[70:73], v138, s[50:51] offset:128
	global_load_dwordx4 v[78:81], v139, s[50:51] offset:128
	global_load_dwordx4 v[86:89], v140, s[50:51] offset:128
	global_load_dwordx4 v[94:97], v125, s[50:51] offset:128
	s_waitcnt lgkmcnt(1)
	v_mfma_f32_32x32x16_bf16 v[50:65], v[112:115], v[120:123], v[50:65]
	s_waitcnt lgkmcnt(0)
	v_mfma_f32_32x32x16_bf16 v[18:33], v[112:115], v[142:145], v[18:33]
	v_mfma_f32_32x32x16_bf16 v[34:49], v[116:119], v[120:123], v[34:49]
	v_mfma_f32_32x32x16_bf16 v[2:17], v[116:119], v[142:145], v[2:17]
	s_barrier
	s_waitcnt vmcnt(11)
	ds_write_b128 v106, v[66:69] offset:16384
	s_waitcnt vmcnt(10)
	ds_write_b128 v106, v[74:77] offset:20480
	s_waitcnt vmcnt(9)
	ds_write_b128 v106, v[82:85] offset:24576
	s_waitcnt vmcnt(8)
	ds_write_b128 v106, v[90:93] offset:28672
	s_waitcnt vmcnt(4)
	s_add_u32 s100, s100, 0x80
	s_addc_u32 s101, s101, 0
	s_mov_b32 m0, s52
	s_nop 0
	global_load_lds_dwordx4 v134, s[100:101]
	global_load_lds_dwordx4 v135, s[100:101] offset:1024
	global_load_lds_dwordx4 v136, s[100:101] offset:2048
	global_load_lds_dwordx4 v137, s[100:101] offset:3072
	s_waitcnt lgkmcnt(0)
	s_barrier
	ds_read_b128 v[112:115], v156 offset:4096
	ds_read_b128 v[120:123], v156
	ds_read_b128 v[116:119], v160 offset:4096
	ds_read_b128 v[148:151], v160
	ds_read_b128 v[142:145], v157
	ds_read_b128 v[152:155], v161
	s_waitcnt lgkmcnt(2)
	v_mfma_f32_32x32x16_bf16 v[34:49], v[112:115], v[148:151], v[34:49]
	v_mfma_f32_32x32x16_bf16 v[2:17], v[112:115], v[116:119], v[2:17]
	ds_read_b128 v[112:115], v157 offset:4096
	v_mfma_f32_32x32x16_bf16 v[18:33], v[120:123], v[116:119], v[18:33]
	ds_read_b128 v[116:119], v161 offset:4096
	s_waitcnt lgkmcnt(1)
	v_mfma_f32_32x32x16_bf16 v[34:49], v[112:115], v[152:155], v[34:49]
	s_waitcnt lgkmcnt(0)
	v_mfma_f32_32x32x16_bf16 v[2:17], v[112:115], v[116:119], v[2:17]
	ds_read_b128 v[112:115], v158
	v_mfma_f32_32x32x16_bf16 v[18:33], v[142:145], v[116:119], v[18:33]
	ds_read_b128 v[116:119], v158 offset:4096
	v_mfma_f32_32x32x16_bf16 v[50:65], v[120:123], v[148:151], v[50:65]
	ds_read_b128 v[120:123], v162
	v_mfma_f32_32x32x16_bf16 v[50:65], v[142:145], v[152:155], v[50:65]
	ds_read_b128 v[142:145], v162 offset:4096
	s_waitcnt lgkmcnt(1)
	v_mfma_f32_32x32x16_bf16 v[50:65], v[112:115], v[120:123], v[50:65]
	s_waitcnt lgkmcnt(0)
	v_mfma_f32_32x32x16_bf16 v[18:33], v[112:115], v[142:145], v[18:33]
	ds_read_b128 v[112:115], v159
	v_mfma_f32_32x32x16_bf16 v[34:49], v[116:119], v[120:123], v[34:49]
	v_mfma_f32_32x32x16_bf16 v[2:17], v[116:119], v[142:145], v[2:17]
	ds_read_b128 v[116:119], v159 offset:4096
	ds_read_b128 v[120:123], v163
	ds_read_b128 v[142:145], v163 offset:4096
	s_add_u32 s50, s50, 0x80
	s_addc_u32 s51, s51, 0
	global_load_dwordx4 v[66:69], v138, s[50:51] offset:128
	global_load_dwordx4 v[74:77], v139, s[50:51] offset:128
	global_load_dwordx4 v[82:85], v140, s[50:51] offset:128
	global_load_dwordx4 v[90:93], v125, s[50:51] offset:128
	s_waitcnt lgkmcnt(1)
	v_mfma_f32_32x32x16_bf16 v[50:65], v[112:115], v[120:123], v[50:65]
	s_waitcnt lgkmcnt(0)
	v_mfma_f32_32x32x16_bf16 v[18:33], v[112:115], v[142:145], v[18:33]
	v_mfma_f32_32x32x16_bf16 v[34:49], v[116:119], v[120:123], v[34:49]
	v_mfma_f32_32x32x16_bf16 v[2:17], v[116:119], v[142:145], v[2:17]
	s_sub_u32 s98, s98, 1
	s_cmp_lg_u32 s98, 0
	s_cbranch_scc1 .Lwd_k_pj
; #define MFMA32(a, b, c) __builtin_amdgcn_mfma_f32_32x32x16_bf16((a), (b), (c), 0, 0, 0)
;     ...
;   for (int kt = 0; kt < NKT; ++kt) {
;     __syncthreads();
; #pragma unroll
;     for (int it = 0; it < 4; ++it) {
;       *(u32x4*)(Xs + (lr + 32 * it) * LSTR + lc) = xr[it];
;       *(u32x4*)(Ys + (lr + 32 * it) * LSTR + lc) = yr[it];
;     }
;     __syncthreads();
;     if (kt + 1 < NKT) {
; #pragma unroll
;       for (int it = 0; it < 4; ++it) {
;         xr[it] = *(const u32x4*)(xg + (size_t)it * 32 * RS + (kt + 1) * 64);
;         yr[it] = *(const u32x4*)(yg + (size_t)it * 32 * RS + (kt + 1) * 64);
;       }
;     }
; #pragma unroll
;     for (int ks = 0; ks < 4; ++ks) {
;       bf16x8 af[TI], bfr[TJ];
; #pragma unroll
;       for (int a = 0; a < TI; ++a) af[a] = *(const bf16x8*)(Xs + (wi0 + a * 32 + fr) * LSTR + ks * 16 + fh);
; #pragma unroll
;       for (int b = 0; b < TJ; ++b) bfr[b] = *(const bf16x8*)(Ys + (wj0 + b * 32 + fr) * LSTR + ks * 16 + fh);
; #pragma unroll
;       for (int a = 0; a < TI; ++a)
; #pragma unroll
;         for (int b = 0; b < TJ; ++b) acc[a][b] = MFMA32(af[a], bfr[b], acc[a][b]);
;     }
;     __builtin_amdgcn_iglp_opt(1);
;   }
; DI void phase_proj(const Params& p, int layer, u16* lds, const int WAVE_S) {
;     ...
;     const int hit = wave >> 1;
;     int type, grp, head;
;     if (ft < 4) { type = 0; grp = 0; head = ft * 2 + hit; }
;     else if (ft == 4) { type = 1; grp = 0; head = hit; }
;     else if (ft == 5) { type = 2; grp = 0; head = hit; }
;     else if (ft < 10) { type = 0; grp = 1; head = (ft - 6) * 2 + hit; }
;     else if (ft == 10) { type = 1; grp = 1; head = hit; }
;     else { type = 2; grp = 1; head = hit; }
	s_barrier
	s_waitcnt vmcnt(11)
	ds_write_b128 v106, v[70:73] offset:16384
	s_waitcnt vmcnt(10)
	ds_write_b128 v106, v[78:81] offset:20480
	s_waitcnt vmcnt(9)
	ds_write_b128 v106, v[86:89] offset:24576
	s_waitcnt vmcnt(8)
	ds_write_b128 v106, v[94:97] offset:28672
	s_waitcnt vmcnt(4)
	s_add_u32 s100, s100, 0x80
	s_addc_u32 s101, s101, 0
	s_mov_b32 m0, s53
	s_nop 0
	global_load_lds_dwordx4 v134, s[100:101]
	global_load_lds_dwordx4 v135, s[100:101] offset:1024
	global_load_lds_dwordx4 v136, s[100:101] offset:2048
	global_load_lds_dwordx4 v137, s[100:101] offset:3072
	s_waitcnt lgkmcnt(0)
	s_barrier
	ds_read_b128 v[112:115], v104 offset:4096
	ds_read_b128 v[120:123], v104
	ds_read_b128 v[116:119], v160 offset:4096
	ds_read_b128 v[148:151], v160
	ds_read_b128 v[142:145], v105
	ds_read_b128 v[152:155], v161
	s_waitcnt lgkmcnt(2)
	v_mfma_f32_32x32x16_bf16 v[34:49], v[112:115], v[148:151], v[34:49]
	v_mfma_f32_32x32x16_bf16 v[2:17], v[112:115], v[116:119], v[2:17]
	ds_read_b128 v[112:115], v105 offset:4096
	v_mfma_f32_32x32x16_bf16 v[18:33], v[120:123], v[116:119], v[18:33]
	ds_read_b128 v[116:119], v161 offset:4096
	s_waitcnt lgkmcnt(1)
	v_mfma_f32_32x32x16_bf16 v[34:49], v[112:115], v[152:155], v[34:49]
	s_waitcnt lgkmcnt(0)
	v_mfma_f32_32x32x16_bf16 v[2:17], v[112:115], v[116:119], v[2:17]
	ds_read_b128 v[112:115], v108
	v_mfma_f32_32x32x16_bf16 v[18:33], v[142:145], v[116:119], v[18:33]
	ds_read_b128 v[116:119], v108 offset:4096
	v_mfma_f32_32x32x16_bf16 v[50:65], v[120:123], v[148:151], v[50:65]
	ds_read_b128 v[120:123], v162
	v_mfma_f32_32x32x16_bf16 v[50:65], v[142:145], v[152:155], v[50:65]
	ds_read_b128 v[142:145], v162 offset:4096
	s_waitcnt lgkmcnt(1)
	v_mfma_f32_32x32x16_bf16 v[50:65], v[112:115], v[120:123], v[50:65]
	s_waitcnt lgkmcnt(0)
	v_mfma_f32_32x32x16_bf16 v[18:33], v[112:115], v[142:145], v[18:33]
	ds_read_b128 v[112:115], v109
	v_mfma_f32_32x32x16_bf16 v[34:49], v[116:119], v[120:123], v[34:49]
	v_mfma_f32_32x32x16_bf16 v[2:17], v[116:119], v[142:145], v[2:17]
	ds_read_b128 v[116:119], v109 offset:4096
	ds_read_b128 v[120:123], v163
	ds_read_b128 v[142:145], v163 offset:4096
	s_waitcnt lgkmcnt(1)
	v_mfma_f32_32x32x16_bf16 v[50:65], v[112:115], v[120:123], v[50:65]
	s_waitcnt lgkmcnt(0)
	v_mfma_f32_32x32x16_bf16 v[18:33], v[112:115], v[142:145], v[18:33]
	v_mfma_f32_32x32x16_bf16 v[34:49], v[116:119], v[120:123], v[34:49]
	v_mfma_f32_32x32x16_bf16 v[2:17], v[116:119], v[142:145], v[2:17]
	s_barrier
	s_waitcnt vmcnt(7)
	ds_write_b128 v106, v[66:69] offset:16384
	s_waitcnt vmcnt(6)
	ds_write_b128 v106, v[74:77] offset:20480
	s_waitcnt vmcnt(5)
	ds_write_b128 v106, v[82:85] offset:24576
	s_waitcnt vmcnt(4)
	ds_write_b128 v106, v[90:93] offset:28672
	s_waitcnt vmcnt(0)
	s_waitcnt lgkmcnt(0)
	s_barrier
	ds_read_b128 v[112:115], v156 offset:4096
	ds_read_b128 v[120:123], v156
	ds_read_b128 v[116:119], v160 offset:4096
	ds_read_b128 v[148:151], v160
	ds_read_b128 v[142:145], v157
	ds_read_b128 v[152:155], v161
	s_waitcnt lgkmcnt(2)
	v_mfma_f32_32x32x16_bf16 v[34:49], v[112:115], v[148:151], v[34:49]
	v_mfma_f32_32x32x16_bf16 v[2:17], v[112:115], v[116:119], v[2:17]
	ds_read_b128 v[112:115], v157 offset:4096
	v_mfma_f32_32x32x16_bf16 v[18:33], v[120:123], v[116:119], v[18:33]
	ds_read_b128 v[116:119], v161 offset:4096
	s_waitcnt lgkmcnt(1)
	v_mfma_f32_32x32x16_bf16 v[34:49], v[112:115], v[152:155], v[34:49]
	s_waitcnt lgkmcnt(0)
	v_mfma_f32_32x32x16_bf16 v[2:17], v[112:115], v[116:119], v[2:17]
	ds_read_b128 v[112:115], v158
	v_mfma_f32_32x32x16_bf16 v[18:33], v[142:145], v[116:119], v[18:33]
	ds_read_b128 v[116:119], v158 offset:4096
	v_mfma_f32_32x32x16_bf16 v[50:65], v[120:123], v[148:151], v[50:65]
	ds_read_b128 v[120:123], v162
	v_mfma_f32_32x32x16_bf16 v[50:65], v[142:145], v[152:155], v[50:65]
	ds_read_b128 v[142:145], v162 offset:4096
	s_waitcnt lgkmcnt(1)
	v_mfma_f32_32x32x16_bf16 v[50:65], v[112:115], v[120:123], v[50:65]
	s_waitcnt lgkmcnt(0)
	v_mfma_f32_32x32x16_bf16 v[18:33], v[112:115], v[142:145], v[18:33]
	ds_read_b128 v[112:115], v159
	v_mfma_f32_32x32x16_bf16 v[34:49], v[116:119], v[120:123], v[34:49]
	v_mfma_f32_32x32x16_bf16 v[2:17], v[116:119], v[142:145], v[2:17]
	ds_read_b128 v[116:119], v159 offset:4096
	ds_read_b128 v[120:123], v163
	ds_read_b128 v[142:145], v163 offset:4096
	s_waitcnt lgkmcnt(1)
	v_mfma_f32_32x32x16_bf16 v[50:65], v[112:115], v[120:123], v[50:65]
	s_waitcnt lgkmcnt(0)
	v_mfma_f32_32x32x16_bf16 v[18:33], v[112:115], v[142:145], v[18:33]
	v_mfma_f32_32x32x16_bf16 v[34:49], v[116:119], v[120:123], v[34:49]
	v_mfma_f32_32x32x16_bf16 v[2:17], v[116:119], v[142:145], v[2:17]
	s_nop 7
	s_nop 7
	v_or_b32_e32 v134, 8, v130
	v_or_b32_e32 v135, 16, v130
	v_or_b32_e32 v136, 24, v130
	v_or_b32_e32 v137, 32, v130
	v_or_b32_e32 v138, 40, v130
	v_or_b32_e32 v139, 48, v130
	v_or_b32_e32 v140, 56, v130
	s_cmp_gt_i32 s48, 3
	s_cbranch_scc0 .LBB0_88
	s_cmp_lt_i32 s48, 5
	s_mov_b64 s[18:19], 0
	s_cbranch_scc1 .LBB0_89
	s_cmp_lg_u32 s48, 5
	s_mov_b64 s[84:85], -1
	s_cbranch_scc0 .LBB0_86
	s_cmp_gt_u32 s48, 9
	s_mov_b64 s[46:47], -1
	s_cbranch_scc0 .LBB0_84
	s_cmp_lg_u32 s48, 10
	s_mov_b64 s[46:47], 0
	s_cselect_b64 s[50:51], -1, 0
